# S2 and S7 unit order: each XCD round covers 4 row panels x 8 column panels (was 8 x 4) so every ACT panel is streamed once
# speedup vs baseline: 1.0404x; 1.0120x over previous
.LBB0_468:
	s_ashr_i32 s1, s1, 3
	s_add_i32 s1, s3, s1
	s_ashr_i32 s2, s1, 31
	s_lshr_b32 s2, s2, 26
	s_add_i32 s2, s1, s2
	s_ashr_i32 s3, s2, 6
	s_andn2_b32 s2, s2, 63
	s_sub_i32 s1, s1, s2
	s_bfe_i32 s2, s1, 0x80000
	s_bfe_u32 s2, s2, 0x3000c
	s_add_i32 s2, s1, s2
	s_bfe_i32 s6, s2, 0x80000
	s_and_b32 s2, s2, 0xf8
	s_sub_i32 s1, s1, s2
	s_lshl_b32 s3, s3, 3
	s_sext_i32_i16 s6, s6
	s_sext_i32_i8 s1, s1
	s_add_i32 s40, s3, s1
	s_ashr_i32 s41, s6, 3
	s_lshr_b32 s98, s41, 2
	s_bfe_u32 s99, s40, 0x10002
	s_and_b32 s100, s41, 3
	s_lshl_b32 s100, s100, 1
	s_or_b32 s41, s100, s99
	s_and_b32 s99, s40, -8
	s_and_b32 s100, s40, 3
	s_lshl_b32 s98, s98, 2
	s_or_b32 s40, s99, s100
	s_or_b32 s40, s40, s98

.LBB0_480:
	s_ashr_i32 s8, s20, 3
	s_add_i32 s8, s24, s8
	s_ashr_i32 s9, s8, 31
	s_lshr_b32 s9, s9, 26
	s_add_i32 s9, s8, s9
	s_ashr_i32 s20, s9, 6
	s_lshl_b32 s20, s20, 3
	s_sub_i32 s21, 64, s20
	s_min_i32 s21, s21, 8
	s_abs_i32 s24, s21
	v_cvt_f32_u32_e32 v0, s24
	s_sub_i32 s26, 0, s24
	s_andn2_b32 s9, s9, 63
	s_sub_i32 s8, s8, s9
	v_rcp_iflag_f32_e32 v0, v0
	s_abs_i32 s9, s8
	s_xor_b32 s25, s8, s21
	s_ashr_i32 s25, s25, 31
	v_mul_f32_e32 v0, 0x4f7ffffe, v0
	v_cvt_u32_f32_e32 v0, v0
	s_nop 0
	v_readfirstlane_b32 s27, v0
	s_mul_i32 s26, s26, s27
	s_mul_hi_u32 s26, s27, s26
	s_add_i32 s27, s27, s26
	s_mul_hi_u32 s26, s9, s27
	s_mul_i32 s27, s26, s24
	s_sub_i32 s9, s9, s27
	s_add_i32 s38, s26, 1
	s_sub_i32 s27, s9, s24
	s_cmp_ge_u32 s9, s24
	s_cselect_b32 s26, s38, s26
	s_cselect_b32 s9, s27, s9
	s_add_i32 s27, s26, 1
	s_cmp_ge_u32 s9, s24
	s_cselect_b32 s9, s27, s26
	s_xor_b32 s9, s9, s25
	s_sub_i32 s38, s9, s25
	s_mul_i32 s9, s38, s21
	s_sub_i32 s8, s8, s9
	s_add_i32 s39, s20, s8
	s_lshr_b32 s98, s38, 2
	s_bfe_u32 s99, s39, 0x10002
	s_and_b32 s100, s38, 3
	s_lshl_b32 s100, s100, 1
	s_or_b32 s38, s100, s99
	s_and_b32 s99, s39, -8
	s_and_b32 s100, s39, 3
	s_lshl_b32 s98, s98, 2
	s_or_b32 s39, s99, s100
	s_or_b32 s39, s39, s98

.LBB0_1468:
	v_lshl_add_u32 v0, v8, 4, s33
	v_ashrrev_i32_e32 v1, 31, v0
	v_lshrrev_b32_e32 v1, 22, v1
	v_add_u32_e32 v1, v0, v1
	v_ashrrev_i32_e32 v9, 10, v1
	v_mul_i32_i24_e32 v1, 0x400, v9
	v_sub_u32_e32 v1, v0, v1
	v_lshrrev_b32_e32 v2, 4, v1
	v_bitop3_b32 v1, v2, v1, 32 bitop3:0x6c
	v_ashrrev_i32_e32 v3, 31, v1
	v_lshrrev_b32_e32 v3, 26, v3
	v_lshlrev_b32_e32 v2, 3, v9
	v_add_u32_e32 v3, v1, v3
	v_and_b32_e32 v2, -16, v2
	v_ashrrev_i32_e32 v10, 6, v3
	v_and_b32_e32 v3, 0xc0, v3
	v_add_u32_e32 v2, v10, v2
	v_lshlrev_b32_e32 v4, 5, v9
	v_sub_u32_e32 v1, v1, v3
	v_mov_b32_e32 v3, 1
	v_and_b32_e32 v11, 32, v4
	v_ashrrev_i16_sdwa v1, v3, sext(v1) dst_sel:DWORD dst_unused:UNUSED_PAD src0_sel:DWORD src1_sel:BYTE_0
	v_lshlrev_b32_e32 v4, 1, v2
	v_lshrrev_b32_e32 v5, 2, v2
	v_and_b32_e32 v6, 3, v10
	s_mov_b32 s5, 0x7fffe0
	v_bfe_i32 v12, v1, 0, 16
	v_and_b32_e32 v4, 24, v4
	v_and_b32_e32 v5, 4, v5
	v_and_or_b32 v6, v2, s5, v6
	s_movk_i32 s4, 0x1600
	v_add_u32_e32 v1, v11, v12
	v_or3_b32 v4, v6, v5, v4
	v_mul_lo_u32 v2, v2, s4
	v_add_lshl_u32 v128, v1, v2, 1
	v_mul_u32_u24_e32 v2, 0x1600, v4
	v_add_u32_e32 v0, 0x2000, v0
	v_add_lshl_u32 v130, v2, v1, 1
	v_ashrrev_i32_e32 v1, 31, v0
	v_lshrrev_b32_e32 v1, 22, v1
	v_add_u32_e32 v1, v0, v1
	v_ashrrev_i32_e32 v13, 10, v1
	v_mul_i32_i24_e32 v1, 0x400, v13
	v_sub_u32_e32 v0, v0, v1
	v_lshrrev_b32_e32 v1, 4, v0
	v_bitop3_b32 v0, v1, v0, 32 bitop3:0x6c
	v_ashrrev_i32_e32 v2, 31, v0
	v_lshrrev_b32_e32 v2, 26, v2
	v_lshlrev_b32_e32 v1, 3, v13
	v_add_u32_e32 v2, v0, v2
	s_add_u32 s0, s54, 0x7000000
	v_and_b32_e32 v1, -16, v1
	v_ashrrev_i32_e32 v14, 6, v2
	v_lshlrev_b32_e32 v4, 5, v13
	s_addc_u32 s1, s55, 0
	v_add_u32_e32 v1, v14, v1
	v_and_b32_e32 v15, 32, v4
	v_and_b32_e32 v4, 3, v14
	s_add_u32 s2, s54, 0xa900000
	v_and_or_b32 v4, v1, s5, v4
	v_readlane_b32 s5, v255, 11
	s_addc_u32 s3, s55, 0
	s_add_i32 s5, s6, s5
	s_ashr_i32 s6, s5, 31
	s_lshr_b32 s6, s6, 26
	s_add_i32 s6, s5, s6
	s_ashr_i32 s7, s6, 6
	s_andn2_b32 s6, s6, 63
	s_sub_i32 s6, s5, s6
	s_bfe_i32 s5, s6, 0x80000
	s_bfe_u32 s5, s5, 0x3000c
	s_add_i32 s8, s6, s5
	v_and_b32_e32 v2, 0xffc0, v2
	s_bfe_i32 s5, s8, 0x80000
	s_and_b32 s8, s8, 0xf8
	v_sub_u32_e32 v0, v0, v2
	s_sub_i32 s6, s6, s8
	v_lshrrev_b16_e32 v2, 7, v0
	s_lshl_b32 s7, s7, 3
	s_sext_i32_i16 s9, s5
	s_sext_i32_i8 s6, s6
	v_and_b32_e32 v2, 1, v2
	s_add_i32 s35, s7, s6
	s_ashr_i32 s6, s9, 3
	v_add_u16_e32 v0, v0, v2
	s_lshr_b32 s5, s9, 3
	s_lshr_b32 s98, s6, 2
	s_bfe_u32 s99, s35, 0x10002
	s_and_b32 s100, s6, 3
	s_lshl_b32 s100, s100, 1
	s_or_b32 s6, s100, s99
	s_and_b32 s99, s35, -8
	s_and_b32 s100, s35, 3
	s_lshl_b32 s98, s98, 2
	s_or_b32 s35, s99, s100
	s_or_b32 s35, s35, s98
	s_mov_b32 s5, s6
	s_mul_hi_i32 s7, s6, 0x2c0000
	s_mul_i32 s6, s6, 0x2c0000
	v_ashrrev_i16_sdwa v0, v3, sext(v0) dst_sel:DWORD dst_unused:UNUSED_PAD src0_sel:DWORD src1_sel:BYTE_0
	v_lshlrev_b32_e32 v2, 1, v1
	v_lshrrev_b32_e32 v3, 2, v1
	s_add_u32 s16, s0, s6
	v_bfe_i32 v16, v0, 0, 16
	v_and_b32_e32 v2, 24, v2
	v_and_b32_e32 v3, 4, v3
	s_addc_u32 s17, s1, s7
	s_add_i32 s22, s33, 0
	v_add_u32_e32 v0, v15, v16
	v_or3_b32 v2, v4, v3, v2
	v_mul_lo_u32 v1, v1, s4
	s_add_i32 m0, s22, 0x10000
	v_add_lshl_u32 v132, v0, v1, 1
	v_mul_u32_u24_e32 v1, 0x1600, v2
	global_load_lds_dwordx4 v130, s[16:17]
	s_add_i32 m0, s22, 0x12000
	v_add_lshl_u32 v134, v1, v0, 1
	s_add_u32 s6, s16, 0x160000
	global_load_lds_dwordx4 v134, s[16:17]
	s_addc_u32 s7, s17, 0
	s_add_i32 m0, s22, 0x14000
	s_mul_i32 s10, s35, 0x2c0000
	global_load_lds_dwordx4 v130, s[6:7]
	s_add_i32 m0, s22, 0x16000
	s_mul_hi_i32 s8, s35, 0x2c0000
	s_add_u32 s14, s2, s10
	s_addc_u32 s15, s3, s8
	s_add_i32 s23, s22, 0x2000
	global_load_lds_dwordx4 v134, s[6:7]
	s_mov_b32 m0, s22
	s_add_u32 s6, s14, 0x160000
	global_load_lds_dwordx4 v128, s[14:15]
	s_mov_b32 m0, s23
	s_addc_u32 s7, s15, 0
	s_add_i32 s24, s22, 0x4000
	global_load_lds_dwordx4 v132, s[14:15]
	s_mov_b32 m0, s24
	s_add_i32 s25, s22, 0x6000
	global_load_lds_dwordx4 v128, s[6:7]
	s_mov_b32 m0, s25
	v_mov_b32_e32 v131, 0
	global_load_lds_dwordx4 v132, s[6:7]
	v_mov_b32_e32 v135, v131
	v_mov_b32_e32 v129, v131
	v_mov_b32_e32 v133, v131
	v_lshl_add_u64 v[6:7], s[16:17], 0, v[130:131]
	s_mov_b32 s26, 0
	v_lshl_add_u64 v[4:5], s[16:17], 0, v[134:135]
	s_mov_b32 s6, 0x16000
	v_lshl_add_u64 v[2:3], s[14:15], 0, v[128:129]
	s_and_b64 vcc, exec, s[60:61]
	v_lshl_add_u64 v[0:1], s[14:15], 0, v[132:133]
	s_cbranch_vccnz .LBB0_1470
	s_barrier

.LBB0_1478:
	s_ashr_i32 s6, s12, 3
	s_add_i32 s6, s18, s6
	s_ashr_i32 s7, s6, 31
	s_lshr_b32 s7, s7, 26
	s_add_i32 s7, s6, s7
	s_ashr_i32 s12, s7, 6
	s_lshl_b32 s12, s12, 3
	s_sub_i32 s13, 64, s12
	s_min_i32 s13, s13, 8
	s_abs_i32 s18, s13
	v_cvt_f32_u32_e32 v0, s18
	s_sub_i32 s20, 0, s18
	s_andn2_b32 s7, s7, 63
	s_sub_i32 s6, s6, s7
	v_rcp_iflag_f32_e32 v0, v0
	s_abs_i32 s7, s6
	s_xor_b32 s19, s6, s13
	s_ashr_i32 s19, s19, 31
	v_mul_f32_e32 v0, 0x4f7ffffe, v0
	v_cvt_u32_f32_e32 v0, v0
	s_nop 0
	v_readfirstlane_b32 s21, v0
	s_mul_i32 s20, s20, s21
	s_mul_hi_u32 s20, s21, s20
	s_add_i32 s21, s21, s20
	s_mul_hi_u32 s20, s7, s21
	s_mul_i32 s21, s20, s18
	s_sub_i32 s7, s7, s21
	s_add_i32 s31, s20, 1
	s_sub_i32 s21, s7, s18
	s_cmp_ge_u32 s7, s18
	s_cselect_b32 s20, s31, s20
	s_cselect_b32 s7, s21, s7
	s_add_i32 s21, s20, 1
	s_cmp_ge_u32 s7, s18
	s_cselect_b32 s7, s21, s20
	s_xor_b32 s7, s7, s19
	s_sub_i32 s31, s7, s19
	s_mul_i32 s7, s31, s13
	s_sub_i32 s6, s6, s7
	s_add_i32 s34, s12, s6
	s_lshr_b32 s98, s31, 2
	s_bfe_u32 s99, s34, 0x10002
	s_and_b32 s100, s31, 3
	s_lshl_b32 s100, s100, 1
	s_or_b32 s31, s100, s99
	s_and_b32 s99, s34, -8
	s_and_b32 s100, s34, 3
	s_lshl_b32 s98, s98, 2
	s_or_b32 s34, s99, s100
	s_or_b32 s34, s34, s98

	.amdhsa_kernel _Z14fwd_megakernel6Params
		.amdhsa_group_segment_fixed_size 0
		.amdhsa_private_segment_fixed_size 0
		.amdhsa_kernarg_size 464
		.amdhsa_user_sgpr_count 2
		.amdhsa_user_sgpr_dispatch_ptr 0
		.amdhsa_user_sgpr_queue_ptr 0
		.amdhsa_user_sgpr_kernarg_segment_ptr 1
		.amdhsa_user_sgpr_dispatch_id 0
		.amdhsa_user_sgpr_kernarg_preload_length 0
		.amdhsa_user_sgpr_kernarg_preload_offset 0
		.amdhsa_user_sgpr_private_segment_size 0
		.amdhsa_uses_dynamic_stack 0
		.amdhsa_enable_private_segment 0
		.amdhsa_system_sgpr_workgroup_id_x 1
		.amdhsa_system_sgpr_workgroup_id_y 0
		.amdhsa_system_sgpr_workgroup_id_z 0
		.amdhsa_system_sgpr_workgroup_info 0
		.amdhsa_system_vgpr_workitem_id 2
		.amdhsa_next_free_vgpr 256
		.amdhsa_next_free_sgpr 102
		.amdhsa_accum_offset 256
		.amdhsa_reserve_vcc 1
		.amdhsa_float_round_mode_32 0
		.amdhsa_float_round_mode_16_64 0
		.amdhsa_float_denorm_mode_32 3
		.amdhsa_float_denorm_mode_16_64 3
		.amdhsa_dx10_clamp 1
		.amdhsa_ieee_mode 1
		.amdhsa_fp16_overflow 0
		.amdhsa_tg_split 0
		.amdhsa_exception_fp_ieee_invalid_op 0
		.amdhsa_exception_fp_denorm_src 0
		.amdhsa_exception_fp_ieee_div_zero 0
		.amdhsa_exception_fp_ieee_overflow 0
		.amdhsa_exception_fp_ieee_underflow 0
		.amdhsa_exception_fp_ieee_inexact 0
		.amdhsa_exception_int_div_zero 0
	.end_amdhsa_kernel

amdhsa.kernels:
  - .agpr_count:     0
    .args:
      - .offset:         0
        .size:           208
        .value_kind:     by_value
      - .offset:         208
        .size:           4
        .value_kind:     hidden_block_count_x
      - .offset:         212
        .size:           4
        .value_kind:     hidden_block_count_y
      - .offset:         216
        .size:           4
        .value_kind:     hidden_block_count_z
      - .offset:         220
        .size:           2
        .value_kind:     hidden_group_size_x
      - .offset:         222
        .size:           2
        .value_kind:     hidden_group_size_y
      - .offset:         224
        .size:           2
        .value_kind:     hidden_group_size_z
      - .offset:         226
        .size:           2
        .value_kind:     hidden_remainder_x
      - .offset:         228
        .size:           2
        .value_kind:     hidden_remainder_y
      - .offset:         230
        .size:           2
        .value_kind:     hidden_remainder_z
      - .offset:         248
        .size:           8
        .value_kind:     hidden_global_offset_x
      - .offset:         256
        .size:           8
        .value_kind:     hidden_global_offset_y
      - .offset:         264
        .size:           8
        .value_kind:     hidden_global_offset_z
      - .offset:         272
        .size:           2
        .value_kind:     hidden_grid_dims
      - .offset:         296
        .size:           8
        .value_kind:     hidden_multigrid_sync_arg
      - .offset:         328
        .size:           4
        .value_kind:     hidden_dynamic_lds_size
    .group_segment_fixed_size: 0
    .kernarg_segment_align: 8
    .kernarg_segment_size: 464
    .language:       OpenCL C
    .language_version:
      - 2
      - 0
    .max_flat_workgroup_size: 512
    .name:           _Z14fwd_megakernel6Params
    .private_segment_fixed_size: 0
    .sgpr_count:     108
    .sgpr_spill_count: 97
    .symbol:         _Z14fwd_megakernel6Params.kd
    .uniform_work_group_size: 1
    .uses_dynamic_stack: false
    .vgpr_count:     256
    .vgpr_spill_count: 0
    .wavefront_size: 64
